# a21 + ret_out epilogue: 8 dwordx2 OB stores -> 4 dwordx4 via v_permlane32_swap, stores deferred to epilogue end, gate-load waits re-derived
# speedup vs baseline: 1.0062x; 1.0007x over previous
.LBB0_864:
	s_or_b64 exec, exec, s[40:41]
	v_lshl_add_u64 v[32:33], v[124:125], 0, s[0:1]
	v_lshl_add_u64 v[32:33], v[32:33], 0, v[126:127]
	v_lshlrev_b64 v[32:33], 1, v[32:33]
	v_lshl_add_u64 v[34:35], s[16:17], 0, v[32:33]
	s_waitcnt lgkmcnt(0)
	s_barrier
	global_load_dwordx2 v[40:41], v[34:35], off
	global_load_dwordx2 v[42:43], v[34:35], off offset:16
	global_load_dwordx2 v[44:45], v[34:35], off offset:32
	ds_read_b32 v37, v130
	global_load_dwordx2 v[46:47], v[34:35], off offset:48
	global_load_dwordx2 v[38:39], v[34:35], off offset:64
	global_load_dwordx2 v[88:89], v[34:35], off offset:80
	v_lshl_add_u64 v[32:33], s[20:21], 0, v[32:33]
	s_mov_b32 s8, s34
	s_waitcnt lgkmcnt(0)
	v_add_f32_e32 v36, v36, v37
	v_fmamk_f32 v36, v36, 0x3c000000, v140
	v_mul_f32_e32 v37, 0x4b800000, v36
	v_cmp_gt_f32_e32 vcc, s44, v36
	s_waitcnt vmcnt(5)
	v_lshlrev_b32_e32 v90, 16, v40
	v_cndmask_b32_e32 v36, v36, v37, vcc
	v_rsq_f32_e32 v36, v36
	v_and_b32_e32 v91, 0xffff0000, v40
	v_lshlrev_b32_e32 v40, 16, v41
	v_and_b32_e32 v41, 0xffff0000, v41
	v_mul_f32_e32 v37, 0x45800000, v36
	v_cndmask_b32_e32 v36, v36, v37, vcc
	s_waitcnt vmcnt(4)
	v_lshlrev_b32_e32 v92, 16, v42
	v_and_b32_e32 v93, 0xffff0000, v42
	v_lshlrev_b32_e32 v42, 16, v43
	v_and_b32_e32 v43, 0xffff0000, v43
	v_mul_f32_e32 v37, 0xbfb8aa3b, v90
	v_mul_f32_e32 v96, 0xbfb8aa3b, v91
	v_mul_f32_e32 v97, 0xbfb8aa3b, v40
	v_mul_f32_e32 v98, 0xbfb8aa3b, v41
	s_waitcnt vmcnt(3)
	v_lshlrev_b32_e32 v94, 16, v44
	v_mul_f32_e32 v99, 0xbfb8aa3b, v92
	v_mul_f32_e32 v100, 0xbfb8aa3b, v93
	v_mul_f32_e32 v101, 0xbfb8aa3b, v42
	v_mul_f32_e32 v102, 0xbfb8aa3b, v43
	v_exp_f32_e32 v37, v37
	v_exp_f32_e32 v96, v96
	v_exp_f32_e32 v97, v97
	v_exp_f32_e32 v98, v98
	v_mul_f32_e32 v103, 0xbfb8aa3b, v94
	v_exp_f32_e32 v99, v99
	v_exp_f32_e32 v100, v100
	v_exp_f32_e32 v101, v101
	v_exp_f32_e32 v102, v102
	v_and_b32_e32 v95, 0xffff0000, v44
	v_lshlrev_b32_e32 v44, 16, v45
	v_and_b32_e32 v45, 0xffff0000, v45
	v_exp_f32_e32 v103, v103
	v_mul_f32_e32 v128, 0xbfb8aa3b, v45
	v_exp_f32_e32 v129, v128
	v_add_f32_e32 v37, 1.0, v37
	v_add_f32_e32 v128, 1.0, v96
	v_add_f32_e32 v142, 1.0, v97
	v_add_f32_e32 v143, 1.0, v98
	v_add_f32_e32 v144, 1.0, v99
	v_add_f32_e32 v145, 1.0, v100
	v_add_f32_e32 v146, 1.0, v101
	v_add_f32_e32 v147, 1.0, v102
	v_rcp_f32_e32 v96, v37
	v_rcp_f32_e32 v97, v128
	v_rcp_f32_e32 v98, v142
	v_rcp_f32_e32 v99, v143
	v_add_f32_e32 v148, 1.0, v103
	v_rcp_f32_e32 v100, v144
	v_rcp_f32_e32 v101, v145
	v_rcp_f32_e32 v102, v146
	v_rcp_f32_e32 v103, v147
	v_mul_f32_e32 v126, 0xbfb8aa3b, v95
	v_mul_f32_e32 v127, 0xbfb8aa3b, v44
	v_exp_f32_e32 v126, v126
	v_exp_f32_e32 v127, v127
	v_pk_mul_f32 v[90:91], v[96:97], v[90:91]
	v_pk_mul_f32 v[40:41], v[98:99], v[40:41]
	v_pk_mul_f32 v[92:93], v[100:101], v[92:93]
	v_pk_mul_f32 v[42:43], v[102:103], v[42:43]
	v_pk_mul_f32 v[16:17], v[16:17], v[90:91]
	v_pk_mul_f32 v[18:19], v[18:19], v[40:41]
	v_pk_mul_f32 v[20:21], v[20:21], v[92:93]
	v_pk_mul_f32 v[22:23], v[22:23], v[42:43]
	v_pk_mul_f32 v[16:17], v[36:37], v[16:17] op_sel_hi:[0,1]
	v_pk_mul_f32 v[18:19], v[36:37], v[18:19] op_sel_hi:[0,1]
	v_pk_mul_f32 v[20:21], v[36:37], v[20:21] op_sel_hi:[0,1]
	v_pk_mul_f32 v[22:23], v[36:37], v[22:23] op_sel_hi:[0,1]
	v_cvt_pk_bf16_f32 v16, v16, v17
	v_cvt_pk_bf16_f32 v17, v18, v19
	v_add_f32_e32 v149, 1.0, v126
	v_add_f32_e32 v150, 1.0, v127
	v_cvt_pk_bf16_f32 v18, v20, v21
	v_cvt_pk_bf16_f32 v19, v22, v23
	v_mov_b32_e32 v228, v16
	v_mov_b32_e32 v229, v17
	v_mov_b32_e32 v230, v18
	v_mov_b32_e32 v231, v19
	v_add_f32_e32 v16, 1.0, v129
	v_rcp_f32_e32 v126, v148
	v_rcp_f32_e32 v127, v149
	v_rcp_f32_e32 v128, v150
	v_rcp_f32_e32 v129, v16
	global_load_dwordx2 v[20:21], v[34:35], off offset:96
	v_pk_mul_f32 v[94:95], v[126:127], v[94:95]
	s_waitcnt vmcnt(3)
	v_lshlrev_b32_e32 v22, 16, v47
	v_pk_mul_f32 v[18:19], v[128:129], v[44:45]
	v_pk_mul_f32 v[16:17], v[24:25], v[94:95]
	v_pk_mul_f32 v[18:19], v[26:27], v[18:19]
	v_pk_mul_f32 v[16:17], v[36:37], v[16:17] op_sel_hi:[0,1]
	v_pk_mul_f32 v[18:19], v[36:37], v[18:19] op_sel_hi:[0,1]
	v_cvt_pk_bf16_f32 v16, v16, v17
	v_cvt_pk_bf16_f32 v17, v18, v19
	v_mov_b32_e32 v232, v16
	v_mov_b32_e32 v233, v17
	v_lshlrev_b32_e32 v16, 16, v46
	v_mul_f32_e32 v17, 0xbfb8aa3b, v16
	v_exp_f32_e32 v18, v17
	v_and_b32_e32 v17, 0xffff0000, v46
	v_mul_f32_e32 v19, 0xbfb8aa3b, v17
	v_exp_f32_e32 v19, v19
	v_and_b32_e32 v23, 0xffff0000, v47
	v_add_f32_e32 v18, 1.0, v18
	v_mul_f32_e32 v24, 0xbfb8aa3b, v22
	v_add_f32_e32 v19, 1.0, v19
	v_mul_f32_e32 v25, 0xbfb8aa3b, v23
	v_rcp_f32_e32 v18, v18
	v_rcp_f32_e32 v19, v19
	v_exp_f32_e32 v24, v24
	v_exp_f32_e32 v25, v25
	s_andn2_b64 vcc, exec, s[38:39]
	v_pk_mul_f32 v[16:17], v[18:19], v[16:17]
	v_add_f32_e32 v18, 1.0, v24
	v_add_f32_e32 v19, 1.0, v25
	v_rcp_f32_e32 v18, v18
	v_rcp_f32_e32 v19, v19
	v_pk_mul_f32 v[16:17], v[28:29], v[16:17]
	v_pk_mul_f32 v[18:19], v[18:19], v[22:23]
	s_nop 0
	v_pk_mul_f32 v[18:19], v[30:31], v[18:19]
	v_pk_mul_f32 v[16:17], v[36:37], v[16:17] op_sel_hi:[0,1]
	v_pk_mul_f32 v[18:19], v[36:37], v[18:19] op_sel_hi:[0,1]
	v_cvt_pk_bf16_f32 v16, v16, v17
	v_cvt_pk_bf16_f32 v17, v18, v19
	global_load_dwordx2 v[18:19], v[34:35], off offset:112
	s_waitcnt vmcnt(3)
	v_lshlrev_b32_e32 v22, 16, v38
	v_and_b32_e32 v23, 0xffff0000, v38
	v_mul_f32_e32 v24, 0xbfb8aa3b, v22
	v_mul_f32_e32 v25, 0xbfb8aa3b, v23
	v_exp_f32_e32 v24, v24
	v_exp_f32_e32 v25, v25
	v_mov_b32_e32 v234, v16
	v_mov_b32_e32 v235, v17
	v_add_f32_e32 v16, 1.0, v24
	v_add_f32_e32 v17, 1.0, v25
	v_lshlrev_b32_e32 v24, 16, v39
	v_and_b32_e32 v25, 0xffff0000, v39
	v_mul_f32_e32 v26, 0xbfb8aa3b, v24
	v_mul_f32_e32 v27, 0xbfb8aa3b, v25
	v_rcp_f32_e32 v16, v16
	v_rcp_f32_e32 v17, v17
	v_exp_f32_e32 v26, v26
	v_exp_f32_e32 v27, v27
	v_pk_mul_f32 v[16:17], v[16:17], v[22:23]
	v_add_f32_e32 v22, 1.0, v26
	v_add_f32_e32 v23, 1.0, v27
	v_rcp_f32_e32 v22, v22
	v_rcp_f32_e32 v23, v23
	v_pk_mul_f32 v[0:1], v[0:1], v[16:17]
	v_pk_mul_f32 v[16:17], v[22:23], v[24:25]
	s_nop 0
	v_pk_mul_f32 v[2:3], v[2:3], v[16:17]
	v_pk_mul_f32 v[0:1], v[36:37], v[0:1] op_sel_hi:[0,1]
	v_pk_mul_f32 v[2:3], v[36:37], v[2:3] op_sel_hi:[0,1]
	v_cvt_pk_bf16_f32 v0, v0, v1
	v_cvt_pk_bf16_f32 v1, v2, v3
	s_waitcnt vmcnt(2)
	v_lshlrev_b32_e32 v2, 16, v88
	v_and_b32_e32 v3, 0xffff0000, v88
	v_mul_f32_e32 v16, 0xbfb8aa3b, v2
	v_mul_f32_e32 v17, 0xbfb8aa3b, v3
	v_exp_f32_e32 v16, v16
	v_exp_f32_e32 v17, v17
	v_mov_b32_e32 v236, v0
	v_mov_b32_e32 v237, v1
	v_add_f32_e32 v0, 1.0, v16
	v_add_f32_e32 v1, 1.0, v17
	v_lshlrev_b32_e32 v16, 16, v89
	v_and_b32_e32 v17, 0xffff0000, v89
	v_mul_f32_e32 v22, 0xbfb8aa3b, v16
	v_mul_f32_e32 v23, 0xbfb8aa3b, v17
	v_rcp_f32_e32 v0, v0
	v_rcp_f32_e32 v1, v1
	v_exp_f32_e32 v22, v22
	v_exp_f32_e32 v23, v23
	v_pk_mul_f32 v[0:1], v[0:1], v[2:3]
	v_add_f32_e32 v2, 1.0, v22
	v_add_f32_e32 v3, 1.0, v23
	v_rcp_f32_e32 v2, v2
	v_rcp_f32_e32 v3, v3
	v_pk_mul_f32 v[0:1], v[4:5], v[0:1]
	v_pk_mul_f32 v[2:3], v[2:3], v[16:17]
	s_nop 0
	v_pk_mul_f32 v[2:3], v[6:7], v[2:3]
	v_pk_mul_f32 v[0:1], v[36:37], v[0:1] op_sel_hi:[0,1]
	v_pk_mul_f32 v[2:3], v[36:37], v[2:3] op_sel_hi:[0,1]
	v_cvt_pk_bf16_f32 v0, v0, v1
	v_cvt_pk_bf16_f32 v1, v2, v3
	s_waitcnt vmcnt(1)
	v_lshlrev_b32_e32 v2, 16, v20
	v_and_b32_e32 v3, 0xffff0000, v20
	v_mul_f32_e32 v4, 0xbfb8aa3b, v2
	v_mul_f32_e32 v5, 0xbfb8aa3b, v3
	v_exp_f32_e32 v4, v4
	v_exp_f32_e32 v5, v5
	v_mov_b32_e32 v238, v0
	v_mov_b32_e32 v239, v1
	v_add_f32_e32 v0, 1.0, v4
	v_add_f32_e32 v1, 1.0, v5
	v_lshlrev_b32_e32 v4, 16, v21
	v_and_b32_e32 v5, 0xffff0000, v21
	v_mul_f32_e32 v6, 0xbfb8aa3b, v4
	v_mul_f32_e32 v7, 0xbfb8aa3b, v5
	v_rcp_f32_e32 v0, v0
	v_rcp_f32_e32 v1, v1
	v_exp_f32_e32 v6, v6
	v_exp_f32_e32 v7, v7
	v_pk_mul_f32 v[0:1], v[0:1], v[2:3]
	v_add_f32_e32 v2, 1.0, v6
	v_add_f32_e32 v3, 1.0, v7
	v_rcp_f32_e32 v2, v2
	v_rcp_f32_e32 v3, v3
	v_pk_mul_f32 v[0:1], v[8:9], v[0:1]
	v_pk_mul_f32 v[2:3], v[2:3], v[4:5]
	s_nop 0
	v_pk_mul_f32 v[2:3], v[10:11], v[2:3]
	v_pk_mul_f32 v[0:1], v[36:37], v[0:1] op_sel_hi:[0,1]
	v_pk_mul_f32 v[2:3], v[36:37], v[2:3] op_sel_hi:[0,1]
	v_cvt_pk_bf16_f32 v0, v0, v1
	v_cvt_pk_bf16_f32 v1, v2, v3
	s_waitcnt vmcnt(0)
	v_lshlrev_b32_e32 v2, 16, v18
	v_and_b32_e32 v3, 0xffff0000, v18
	v_mul_f32_e32 v4, 0xbfb8aa3b, v2
	v_mul_f32_e32 v5, 0xbfb8aa3b, v3
	v_exp_f32_e32 v4, v4
	v_exp_f32_e32 v5, v5
	v_mov_b32_e32 v240, v0
	v_mov_b32_e32 v241, v1
	v_add_f32_e32 v0, 1.0, v4
	v_add_f32_e32 v1, 1.0, v5
	v_lshlrev_b32_e32 v4, 16, v19
	v_and_b32_e32 v5, 0xffff0000, v19
	v_mul_f32_e32 v6, 0xbfb8aa3b, v4
	v_mul_f32_e32 v7, 0xbfb8aa3b, v5
	v_rcp_f32_e32 v0, v0
	v_rcp_f32_e32 v1, v1
	v_exp_f32_e32 v6, v6
	v_exp_f32_e32 v7, v7
	v_pk_mul_f32 v[0:1], v[0:1], v[2:3]
	v_add_f32_e32 v2, 1.0, v6
	v_add_f32_e32 v3, 1.0, v7
	v_rcp_f32_e32 v2, v2
	v_rcp_f32_e32 v3, v3
	v_pk_mul_f32 v[0:1], v[12:13], v[0:1]
	v_pk_mul_f32 v[2:3], v[2:3], v[4:5]
	s_nop 0
	v_pk_mul_f32 v[2:3], v[14:15], v[2:3]
	v_pk_mul_f32 v[0:1], v[36:37], v[0:1] op_sel_hi:[0,1]
	v_pk_mul_f32 v[2:3], v[36:37], v[2:3] op_sel_hi:[0,1]
	v_cvt_pk_bf16_f32 v0, v0, v1
	v_cvt_pk_bf16_f32 v1, v2, v3
	v_mov_b32_e32 v242, v0
	v_mov_b32_e32 v243, v1
	v_lshrrev_b32_e32 v34, 2, v104
	v_and_b32_e32 v34, 8, v34
	v_mov_b32_e32 v35, 0
	v_lshl_add_u64 v[32:33], v[32:33], 0, v[34:35]
	s_nop 1
	v_permlane32_swap_b32_e32 v228, v230
	v_permlane32_swap_b32_e32 v229, v231
	v_permlane32_swap_b32_e32 v232, v234
	v_permlane32_swap_b32_e32 v233, v235
	v_permlane32_swap_b32_e32 v236, v238
	v_permlane32_swap_b32_e32 v237, v239
	v_permlane32_swap_b32_e32 v240, v242
	v_permlane32_swap_b32_e32 v241, v243
	global_store_dwordx4 v[32:33], v[228:231], off
	global_store_dwordx4 v[32:33], v[232:235], off offset:32
	global_store_dwordx4 v[32:33], v[236:239], off offset:64
	global_store_dwordx4 v[32:33], v[240:243], off offset:96
	s_barrier
	s_cbranch_vccz .LBB0_871
